# phase 0: the 80 third row items reassigned from workgroups 0..79 (9 transpose tiles) to workgroups 176..255 (8 tiles)
# baseline (speedup 1.0000x reference)
.LBB0_468:
	s_or_b64 exec, exec, s[14:15]
	v_readlane_b32 s0, v254, 62
	s_add_i32 s29, s29, s0
	v_add_u32_e32 v74, s28, v74
	s_cmpk_lg_u32 s0, 0x100
	s_cbranch_scc1 .Lr3_std
	s_cmpk_lt_i32 s29, 0x200
	s_cbranch_scc1 .LBB0_469
	s_cmpk_lt_i32 s29, 0x2b0
	s_cbranch_scc1 .LBB0_506
	s_cmpk_gt_i32 s29, 0x2ff
	s_cbranch_scc1 .LBB0_506
	s_lshl_b32 s1, s29, 1
	s_sub_i32 s1, 0x4ff, s1
	s_lshl_b32 s1, s1, 5
	v_add_u32_e32 v74, s1, v74
	s_branch .LBB0_469
.Lr3_std:
	s_cmpk_gt_i32 s29, 0x24f
	s_cbranch_scc1 .LBB0_506

.Lrow_xready:
	v_pk_mul_f32 v[58:59], v[178:179], v[178:179]
	v_pk_mul_f32 v[60:61], v[194:195], v[194:195]
	v_pk_mul_f32 v[62:63], v[210:211], v[210:211]
	v_pk_mul_f32 v[64:65], v[232:233], v[232:233]
	v_pk_fma_f32 v[58:59], v[180:181], v[180:181], v[58:59]
	v_pk_fma_f32 v[60:61], v[196:197], v[196:197], v[60:61]
	v_pk_fma_f32 v[62:63], v[212:213], v[212:213], v[62:63]
	v_pk_fma_f32 v[64:65], v[234:235], v[234:235], v[64:65]
	v_pk_fma_f32 v[58:59], v[182:183], v[182:183], v[58:59]
	v_pk_fma_f32 v[60:61], v[198:199], v[198:199], v[60:61]
	v_pk_fma_f32 v[62:63], v[214:215], v[214:215], v[62:63]
	v_pk_fma_f32 v[64:65], v[236:237], v[236:237], v[64:65]
	v_pk_fma_f32 v[58:59], v[184:185], v[184:185], v[58:59]
	v_pk_fma_f32 v[60:61], v[200:201], v[200:201], v[60:61]
	v_pk_fma_f32 v[62:63], v[216:217], v[216:217], v[62:63]
	v_pk_fma_f32 v[64:65], v[238:239], v[238:239], v[64:65]
	v_pk_fma_f32 v[58:59], v[186:187], v[186:187], v[58:59]
	v_pk_fma_f32 v[60:61], v[202:203], v[202:203], v[60:61]
	v_pk_fma_f32 v[62:63], v[218:219], v[218:219], v[62:63]
	v_pk_fma_f32 v[64:65], v[240:241], v[240:241], v[64:65]
	v_pk_fma_f32 v[58:59], v[188:189], v[188:189], v[58:59]
	v_pk_fma_f32 v[60:61], v[204:205], v[204:205], v[60:61]
	v_pk_fma_f32 v[62:63], v[220:221], v[220:221], v[62:63]
	v_pk_fma_f32 v[64:65], v[242:243], v[242:243], v[64:65]
	v_pk_fma_f32 v[58:59], v[190:191], v[190:191], v[58:59]
	v_pk_fma_f32 v[60:61], v[206:207], v[206:207], v[60:61]
	v_pk_fma_f32 v[62:63], v[222:223], v[222:223], v[62:63]
	v_pk_fma_f32 v[64:65], v[244:245], v[244:245], v[64:65]
	v_pk_fma_f32 v[58:59], v[192:193], v[192:193], v[58:59]
	v_pk_fma_f32 v[60:61], v[208:209], v[208:209], v[60:61]
	v_pk_fma_f32 v[62:63], v[224:225], v[224:225], v[62:63]
	v_pk_fma_f32 v[64:65], v[246:247], v[246:247], v[64:65]
	v_add_f32_e32 v58, v58, v59
	v_add_f32_e32 v60, v60, v61
	v_add_f32_e32 v62, v62, v63
	v_add_f32_e32 v64, v64, v65
	v_add_f32_dpp v58, v58, v58 quad_perm:[1,0,3,2] row_mask:0xf bank_mask:0xf
	v_add_f32_dpp v60, v60, v60 quad_perm:[1,0,3,2] row_mask:0xf bank_mask:0xf
	v_add_f32_dpp v62, v62, v62 quad_perm:[1,0,3,2] row_mask:0xf bank_mask:0xf
	v_add_f32_dpp v64, v64, v64 quad_perm:[1,0,3,2] row_mask:0xf bank_mask:0xf
	v_add_f32_dpp v58, v58, v58 quad_perm:[2,3,0,1] row_mask:0xf bank_mask:0xf
	v_add_f32_dpp v60, v60, v60 quad_perm:[2,3,0,1] row_mask:0xf bank_mask:0xf
	v_add_f32_dpp v62, v62, v62 quad_perm:[2,3,0,1] row_mask:0xf bank_mask:0xf
	v_add_f32_dpp v64, v64, v64 quad_perm:[2,3,0,1] row_mask:0xf bank_mask:0xf
	v_add_f32_dpp v58, v58, v58 row_half_mirror row_mask:0xf bank_mask:0xf
	v_add_f32_dpp v60, v60, v60 row_half_mirror row_mask:0xf bank_mask:0xf
	v_add_f32_dpp v62, v62, v62 row_half_mirror row_mask:0xf bank_mask:0xf
	v_add_f32_dpp v64, v64, v64 row_half_mirror row_mask:0xf bank_mask:0xf
	v_add_f32_dpp v58, v58, v58 row_mirror row_mask:0xf bank_mask:0xf
	v_add_f32_dpp v60, v60, v60 row_mirror row_mask:0xf bank_mask:0xf
	v_add_f32_dpp v62, v62, v62 row_mirror row_mask:0xf bank_mask:0xf
	v_add_f32_dpp v64, v64, v64 row_mirror row_mask:0xf bank_mask:0xf
	v_add_f32_dpp v58, v58, v58 row_bcast:15 row_mask:0xa bank_mask:0xf
	v_add_f32_dpp v60, v60, v60 row_bcast:15 row_mask:0xa bank_mask:0xf
	v_add_f32_dpp v62, v62, v62 row_bcast:15 row_mask:0xa bank_mask:0xf
	v_add_f32_dpp v64, v64, v64 row_bcast:15 row_mask:0xa bank_mask:0xf
	v_add_f32_dpp v58, v58, v58 row_bcast:31 row_mask:0xc bank_mask:0xf
	v_add_f32_dpp v60, v60, v60 row_bcast:31 row_mask:0xc bank_mask:0xf
	v_add_f32_dpp v62, v62, v62 row_bcast:31 row_mask:0xc bank_mask:0xf
	v_add_f32_dpp v64, v64, v64 row_bcast:31 row_mask:0xc bank_mask:0xf
	s_nop 1
	v_readlane_b32 s22, v58, 63
	v_readlane_b32 s23, v60, 63
	v_readlane_b32 s24, v62, 63
	v_readlane_b32 s25, v64, 63
	s_nop 1
	v_fma_f32 v104, s22, v162, v172
	v_fma_f32 v106, s23, v162, v172
	v_fma_f32 v108, s24, v162, v172
	v_fma_f32 v110, s25, v162, v172
	v_rsq_f32_e32 v104, v104
	v_rsq_f32_e32 v106, v106
	v_rsq_f32_e32 v108, v108
	v_rsq_f32_e32 v110, v110
	s_waitcnt vmcnt(0)
	v_pk_mul_f32 v[178:179], v[178:179], v[104:105] op_sel_hi:[1,0]
	v_pk_mul_f32 v[180:181], v[180:181], v[104:105] op_sel_hi:[1,0]
	v_pk_mul_f32 v[182:183], v[182:183], v[104:105] op_sel_hi:[1,0]
	v_pk_mul_f32 v[184:185], v[184:185], v[104:105] op_sel_hi:[1,0]
	v_pk_mul_f32 v[186:187], v[186:187], v[104:105] op_sel_hi:[1,0]
	v_pk_mul_f32 v[188:189], v[188:189], v[104:105] op_sel_hi:[1,0]
	v_pk_mul_f32 v[190:191], v[190:191], v[104:105] op_sel_hi:[1,0]
	v_pk_mul_f32 v[192:193], v[192:193], v[104:105] op_sel_hi:[1,0]
	v_pk_mul_f32 v[90:91], v[2:3], v[178:179]
	v_pk_mul_f32 v[82:83], v[4:5], v[180:181]
	v_pk_mul_f32 v[88:89], v[6:7], v[182:183]
	v_pk_mul_f32 v[80:81], v[8:9], v[184:185]
	v_pk_mul_f32 v[86:87], v[10:11], v[186:187]
	v_pk_mul_f32 v[78:79], v[12:13], v[188:189]
	v_pk_mul_f32 v[84:85], v[14:15], v[190:191]
	v_pk_mul_f32 v[76:77], v[16:17], v[192:193]
	v_cvt_pk_bf16_f32 v178, v90, v91
	v_cvt_pk_bf16_f32 v179, v82, v83
	v_cvt_pk_bf16_f32 v182, v88, v89
	v_cvt_pk_bf16_f32 v183, v80, v81
	v_cvt_pk_bf16_f32 v186, v86, v87
	v_cvt_pk_bf16_f32 v187, v78, v79
	v_cvt_pk_bf16_f32 v190, v84, v85
	v_cvt_pk_bf16_f32 v191, v76, v77
	global_store_dwordx2 v[160:161], v[178:179], off offset:-4096
	global_store_dwordx2 v[160:161], v[182:183], off offset:-3584
	global_store_dwordx2 v[160:161], v[186:187], off offset:-3072
	global_store_dwordx2 v[160:161], v[190:191], off offset:-2560
	v_pk_mul_f32 v[194:195], v[194:195], v[106:107] op_sel_hi:[1,0]
	v_pk_mul_f32 v[196:197], v[196:197], v[106:107] op_sel_hi:[1,0]
	v_pk_mul_f32 v[198:199], v[198:199], v[106:107] op_sel_hi:[1,0]
	v_pk_mul_f32 v[200:201], v[200:201], v[106:107] op_sel_hi:[1,0]
	v_pk_mul_f32 v[202:203], v[202:203], v[106:107] op_sel_hi:[1,0]
	v_pk_mul_f32 v[204:205], v[204:205], v[106:107] op_sel_hi:[1,0]
	v_pk_mul_f32 v[206:207], v[206:207], v[106:107] op_sel_hi:[1,0]
	v_pk_mul_f32 v[208:209], v[208:209], v[106:107] op_sel_hi:[1,0]
	v_pk_mul_f32 v[102:103], v[2:3], v[194:195]
	v_pk_mul_f32 v[96:97], v[4:5], v[196:197]
	v_pk_mul_f32 v[100:101], v[6:7], v[198:199]
	v_pk_mul_f32 v[94:95], v[8:9], v[200:201]
	v_pk_mul_f32 v[98:99], v[10:11], v[202:203]
	v_pk_mul_f32 v[92:93], v[12:13], v[204:205]
	v_pk_mul_f32 v[20:21], v[14:15], v[206:207]
	v_pk_mul_f32 v[18:19], v[16:17], v[208:209]
	v_cvt_pk_bf16_f32 v194, v102, v103
	v_cvt_pk_bf16_f32 v195, v96, v97
	v_cvt_pk_bf16_f32 v198, v100, v101
	v_cvt_pk_bf16_f32 v199, v94, v95
	v_cvt_pk_bf16_f32 v202, v98, v99
	v_cvt_pk_bf16_f32 v203, v92, v93
	v_cvt_pk_bf16_f32 v206, v20, v21
	v_cvt_pk_bf16_f32 v207, v18, v19
	global_store_dwordx2 v[160:161], v[194:195], off offset:-2048
	global_store_dwordx2 v[160:161], v[198:199], off offset:-1536
	global_store_dwordx2 v[160:161], v[202:203], off offset:-1024
	global_store_dwordx2 v[160:161], v[206:207], off offset:-512
	v_pk_mul_f32 v[210:211], v[210:211], v[108:109] op_sel_hi:[1,0]
	v_pk_mul_f32 v[212:213], v[212:213], v[108:109] op_sel_hi:[1,0]
	v_pk_mul_f32 v[214:215], v[214:215], v[108:109] op_sel_hi:[1,0]
	v_pk_mul_f32 v[216:217], v[216:217], v[108:109] op_sel_hi:[1,0]
	v_pk_mul_f32 v[218:219], v[218:219], v[108:109] op_sel_hi:[1,0]
	v_pk_mul_f32 v[220:221], v[220:221], v[108:109] op_sel_hi:[1,0]
	v_pk_mul_f32 v[222:223], v[222:223], v[108:109] op_sel_hi:[1,0]
	v_pk_mul_f32 v[224:225], v[224:225], v[108:109] op_sel_hi:[1,0]
	v_pk_mul_f32 v[34:35], v[2:3], v[210:211]
	v_pk_mul_f32 v[28:29], v[4:5], v[212:213]
	v_pk_mul_f32 v[40:41], v[6:7], v[214:215]
	v_pk_mul_f32 v[30:31], v[8:9], v[216:217]
	v_pk_mul_f32 v[36:37], v[10:11], v[218:219]
	v_pk_mul_f32 v[32:33], v[12:13], v[220:221]
	v_pk_mul_f32 v[24:25], v[14:15], v[222:223]
	v_pk_mul_f32 v[22:23], v[16:17], v[224:225]
	v_cvt_pk_bf16_f32 v210, v34, v35
	v_cvt_pk_bf16_f32 v211, v28, v29
	v_cvt_pk_bf16_f32 v214, v40, v41
	v_cvt_pk_bf16_f32 v215, v30, v31
	v_cvt_pk_bf16_f32 v218, v36, v37
	v_cvt_pk_bf16_f32 v219, v32, v33
	v_cvt_pk_bf16_f32 v222, v24, v25
	v_cvt_pk_bf16_f32 v223, v22, v23
	global_store_dwordx2 v[160:161], v[210:211], off
	global_store_dwordx2 v[160:161], v[214:215], off offset:512
	global_store_dwordx2 v[160:161], v[218:219], off offset:1024
	global_store_dwordx2 v[160:161], v[222:223], off offset:1536
	v_pk_mul_f32 v[232:233], v[232:233], v[110:111] op_sel_hi:[1,0]
	v_pk_mul_f32 v[234:235], v[234:235], v[110:111] op_sel_hi:[1,0]
	v_pk_mul_f32 v[236:237], v[236:237], v[110:111] op_sel_hi:[1,0]
	v_pk_mul_f32 v[238:239], v[238:239], v[110:111] op_sel_hi:[1,0]
	v_pk_mul_f32 v[240:241], v[240:241], v[110:111] op_sel_hi:[1,0]
	v_pk_mul_f32 v[242:243], v[242:243], v[110:111] op_sel_hi:[1,0]
	v_pk_mul_f32 v[244:245], v[244:245], v[110:111] op_sel_hi:[1,0]
	v_pk_mul_f32 v[246:247], v[246:247], v[110:111] op_sel_hi:[1,0]
	v_pk_mul_f32 v[42:43], v[2:3], v[232:233]
	v_pk_mul_f32 v[38:39], v[4:5], v[234:235]
	v_pk_mul_f32 v[48:49], v[6:7], v[236:237]
	v_pk_mul_f32 v[44:45], v[8:9], v[238:239]
	v_pk_mul_f32 v[56:57], v[10:11], v[240:241]
	v_pk_mul_f32 v[50:51], v[12:13], v[242:243]
	v_pk_mul_f32 v[52:53], v[14:15], v[244:245]
	v_pk_mul_f32 v[46:47], v[16:17], v[246:247]
	v_cvt_pk_bf16_f32 v232, v42, v43
	v_cvt_pk_bf16_f32 v233, v38, v39
	v_cvt_pk_bf16_f32 v236, v48, v49
	v_cvt_pk_bf16_f32 v237, v44, v45
	v_cvt_pk_bf16_f32 v240, v56, v57
	v_cvt_pk_bf16_f32 v241, v50, v51
	v_cvt_pk_bf16_f32 v244, v52, v53
	v_cvt_pk_bf16_f32 v245, v46, v47
	global_store_dwordx2 v[160:161], v[232:233], off offset:2048
	global_store_dwordx2 v[160:161], v[236:237], off offset:2560
	global_store_dwordx2 v[160:161], v[240:241], off offset:3072
	global_store_dwordx2 v[160:161], v[244:245], off offset:3584
	v_readlane_b32 s30, v254, 62
	v_add_u32_e32 v159, s28, v74
	s_cmpk_lg_u32 s30, 0x100
	s_cbranch_scc1 .Lpf_std
	s_add_i32 s30, s29, s30
	s_cmpk_lt_i32 s30, 0x200
	s_cbranch_scc1 .Lpf_go
	s_cmpk_lt_i32 s30, 0x2b0
	s_cbranch_scc1 .Lrow_nopf
	s_cmpk_gt_i32 s30, 0x2ff
	s_cbranch_scc1 .Lrow_nopf
	s_lshl_b32 s26, s30, 1
	s_sub_i32 s26, 0x4ff, s26
	s_lshl_b32 s26, s26, 5
	v_add_u32_e32 v159, s26, v159
	s_branch .Lpf_go
.Lpf_std:
	s_add_i32 s30, s29, s30
	s_cmpk_gt_i32 s30, 0x24f
	s_cbranch_scc1 .Lrow_nopf
.Lpf_go:
	v_cmp_lt_i32_e64 s[2:3], s49, v159
	s_movk_i32 s26, 0x3fff
	v_cmp_lt_i32_e64 s[26:27], s26, v159
	v_add_u32_e32 v160, 0xffffc000, v159
	v_add_u32_e32 v161, 0xffffbe00, v159
	v_mov_b32_e32 v164, 0x1000
	v_cndmask_b32_e64 v162, v248, v250, s[26:27]
	v_cndmask_b32_e64 v163, v249, v251, s[26:27]
	v_cndmask_b32_e64 v160, v159, v160, s[26:27]
	v_cndmask_b32_e64 v162, v162, v252, s[2:3]
	v_cndmask_b32_e64 v163, v163, v253, s[2:3]
	v_cndmask_b32_e64 v160, v160, v161, s[2:3]
	v_mov_b32_e32 v166, 0x3000
	v_lshl_add_u32 v164, v160, 12, v164
	v_lshl_add_u32 v166, v160, 12, v166
	v_mov_b32_e32 v165, v26
	v_mov_b32_e32 v167, v26
	v_lshl_add_u64 v[164:165], v[162:163], 0, v[164:165]
	v_lshl_add_u64 v[166:167], v[162:163], 0, v[166:167]
	global_load_dwordx4 v[178:181], v[164:165], off offset:-4096 nt
	global_load_dwordx4 v[182:185], v[164:165], off offset:-3072 nt
	global_load_dwordx4 v[186:189], v[164:165], off offset:-2048 nt
	global_load_dwordx4 v[190:193], v[164:165], off offset:-1024 nt
	global_load_dwordx4 v[194:197], v[164:165], off nt
	global_load_dwordx4 v[198:201], v[164:165], off offset:1024 nt
	global_load_dwordx4 v[202:205], v[164:165], off offset:2048 nt
	global_load_dwordx4 v[206:209], v[164:165], off offset:3072 nt
	global_load_dwordx4 v[210:213], v[166:167], off offset:-4096 nt
	global_load_dwordx4 v[214:217], v[166:167], off offset:-3072 nt
	global_load_dwordx4 v[218:221], v[166:167], off offset:-2048 nt
	global_load_dwordx4 v[222:225], v[166:167], off offset:-1024 nt
	global_load_dwordx4 v[232:235], v[166:167], off nt
	global_load_dwordx4 v[236:239], v[166:167], off offset:1024 nt
	global_load_dwordx4 v[240:243], v[166:167], off offset:2048 nt
	global_load_dwordx4 v[244:247], v[166:167], off offset:3072 nt
